# P0 x-copy writes the bf16 copy with write-through (sc1) stores, like the norm
# baseline (speedup 1.0000x reference)
; __device__ __forceinline__ void p0_phase(const Args& a, LAS unsigned char* lds, int tid, int lane, int wave, int bid, int G) {
;     ...
;         for (;;) {
;             if (threadIdx.x == 0) slot[0] = __hip_atomic_fetch_add(head, 1u, __ATOMIC_RELAXED, __HIP_MEMORY_SCOPE_AGENT);
;             __syncthreads();
;             const int q = (int)slot[0];
;             __syncthreads();
;             if (q >= M / 64) break;
;             asm volatile("" : "+v"(tid)); lane = tid & 63;
;             f32x4 v[8][4];
; #pragma unroll
;             for (int r = 0; r < 8; ++r) { const int row = q * 64 + wave * 8 + r;
;                 const float* xrow = row < MP ? a.in[0] + (size_t)row * D : a.in[1] + (size_t)(row - MP) * D;
; #pragma unroll
;                 for (int j = 0; j < 4; ++j) v[r][j] = __builtin_nontemporal_load((const f32x4*)xrow + 64 * j + lane); }
; #pragma unroll
;             for (int r = 0; r < 8; ++r) { const int row = q * 64 + wave * 8 + r;
; #pragma unroll
;                 for (int j = 0; j < 4; ++j) { u32x2 o; o.x = pk_bf16(v[r][j].x, v[r][j].y); o.y = pk_bf16(v[r][j].z, v[r][j].w); *((u32x2*)(XB0 + (size_t)row * D) + 64 * j + lane) = o; } }
;         }
.LBB0_124:
	global_load_dwordx4 v[118:121], v116, s[26:27] nt
	global_load_dwordx4 v[122:125], v116, s[26:27] offset:1024 nt
	global_load_dwordx4 v[126:129], v116, s[26:27] offset:2048 nt
	global_load_dwordx4 v[130:133], v116, s[26:27] offset:3072 nt
	v_lshlrev_b32_e32 v112, 3, v112
	v_lshl_add_u64 v[116:117], s[6:7], 0, v[112:113]
	s_lshl_b64 s[22:23], s[22:23], 11
	v_lshl_add_u64 v[134:135], v[116:117], 0, s[22:23]
	s_waitcnt vmcnt(28)
	v_cvt_pk_bf16_f32 v32, v32, v33
	v_cvt_pk_bf16_f32 v33, v34, v35
	s_lshl_b64 s[22:23], s[24:25], 11
	global_store_dwordx2 v[134:135], v[32:33], off offset:1536 sc1
	v_lshl_add_u64 v[32:33], v[116:117], 0, s[22:23]
	s_waitcnt vmcnt(25)
	v_cvt_pk_bf16_f32 v20, v20, v21
	v_cvt_pk_bf16_f32 v21, v22, v23
	s_lshl_b64 s[20:21], s[20:21], 11
	global_store_dwordx2 v[32:33], v[20:21], off offset:1536 sc1
	v_lshl_add_u64 v[20:21], v[116:117], 0, s[20:21]
	s_waitcnt vmcnt(22)
	v_cvt_pk_bf16_f32 v16, v16, v17
	v_cvt_pk_bf16_f32 v17, v18, v19
	s_lshl_b64 s[18:19], s[18:19], 11
	global_store_dwordx2 v[20:21], v[16:17], off offset:1536 sc1
	v_lshl_add_u64 v[16:17], v[116:117], 0, s[18:19]
	s_waitcnt vmcnt(19)
	v_cvt_pk_bf16_f32 v12, v12, v13
	v_cvt_pk_bf16_f32 v13, v14, v15
	s_lshl_b64 s[16:17], s[16:17], 11
	global_store_dwordx2 v[16:17], v[12:13], off offset:1536 sc1
	v_lshl_add_u64 v[12:13], v[116:117], 0, s[16:17]
	s_waitcnt vmcnt(16)
	v_cvt_pk_bf16_f32 v8, v8, v9
	v_cvt_pk_bf16_f32 v9, v10, v11
	s_lshl_b64 s[14:15], s[14:15], 11
	global_store_dwordx2 v[12:13], v[8:9], off offset:1536 sc1
	v_lshl_add_u64 v[8:9], v[116:117], 0, s[14:15]
	s_waitcnt vmcnt(13)
	v_cvt_pk_bf16_f32 v0, v0, v1
	v_cvt_pk_bf16_f32 v1, v2, v3
	s_lshl_b64 s[12:13], s[12:13], 11
	global_store_dwordx2 v[8:9], v[0:1], off offset:1536 sc1
	v_lshl_add_u64 v[0:1], v[116:117], 0, s[12:13]
	s_waitcnt vmcnt(13)
	v_cvt_pk_bf16_f32 v2, v84, v85
	v_cvt_pk_bf16_f32 v3, v86, v87
	global_store_dwordx2 v[0:1], v[2:3], off sc1
	s_waitcnt vmcnt(13)
	v_cvt_pk_bf16_f32 v2, v56, v57
	v_cvt_pk_bf16_f32 v3, v58, v59
	global_store_dwordx2 v[0:1], v[2:3], off offset:512 sc1
	s_waitcnt vmcnt(13)
	v_cvt_pk_bf16_f32 v2, v28, v29
	v_cvt_pk_bf16_f32 v3, v30, v31
	global_store_dwordx2 v[0:1], v[2:3], off offset:1024 sc1
	s_waitcnt vmcnt(13)
	v_cvt_pk_bf16_f32 v2, v4, v5
	v_cvt_pk_bf16_f32 v3, v6, v7
	s_lshl_b64 s[10:11], s[10:11], 11
	v_cvt_pk_bf16_f32 v108, v108, v109
	v_cvt_pk_bf16_f32 v109, v110, v111
	v_cvt_pk_bf16_f32 v34, v104, v105
	v_cvt_pk_bf16_f32 v35, v106, v107
	v_cvt_pk_bf16_f32 v22, v100, v101
	v_cvt_pk_bf16_f32 v23, v102, v103
	v_cvt_pk_bf16_f32 v18, v96, v97
	v_cvt_pk_bf16_f32 v19, v98, v99
	v_cvt_pk_bf16_f32 v14, v92, v93
	v_cvt_pk_bf16_f32 v15, v94, v95
	v_cvt_pk_bf16_f32 v10, v80, v81
	v_cvt_pk_bf16_f32 v11, v82, v83
	global_store_dwordx2 v[0:1], v[2:3], off offset:1536 sc1
	v_lshl_add_u64 v[0:1], v[116:117], 0, s[10:11]
	global_store_dwordx2 v[134:135], v[108:109], off sc1
	v_cvt_pk_bf16_f32 v88, v88, v89
	v_cvt_pk_bf16_f32 v89, v90, v91
	global_store_dwordx2 v[32:33], v[34:35], off sc1
	v_cvt_pk_bf16_f32 v34, v76, v77
	v_cvt_pk_bf16_f32 v35, v78, v79
	global_store_dwordx2 v[20:21], v[22:23], off sc1
	v_cvt_pk_bf16_f32 v22, v72, v73
	v_cvt_pk_bf16_f32 v23, v74, v75
	global_store_dwordx2 v[16:17], v[18:19], off sc1
	v_cvt_pk_bf16_f32 v18, v68, v69
	v_cvt_pk_bf16_f32 v19, v70, v71
	global_store_dwordx2 v[12:13], v[14:15], off sc1
	v_cvt_pk_bf16_f32 v14, v64, v65
	v_cvt_pk_bf16_f32 v15, v66, v67
	global_store_dwordx2 v[8:9], v[10:11], off sc1
	s_waitcnt vmcnt(19)
	v_cvt_pk_bf16_f32 v2, v118, v119
	v_cvt_pk_bf16_f32 v3, v120, v121
	v_cvt_pk_bf16_f32 v10, v52, v53
	v_cvt_pk_bf16_f32 v11, v54, v55
	global_store_dwordx2 v[0:1], v[2:3], off sc1
	s_waitcnt vmcnt(19)
	v_cvt_pk_bf16_f32 v2, v122, v123
	v_cvt_pk_bf16_f32 v3, v124, v125
	global_store_dwordx2 v[134:135], v[88:89], off offset:512 sc1
	v_cvt_pk_bf16_f32 v60, v60, v61
	v_cvt_pk_bf16_f32 v61, v62, v63
	global_store_dwordx2 v[32:33], v[34:35], off offset:512 sc1
	v_cvt_pk_bf16_f32 v34, v48, v49
	v_cvt_pk_bf16_f32 v35, v50, v51
	global_store_dwordx2 v[20:21], v[22:23], off offset:512 sc1
	v_cvt_pk_bf16_f32 v22, v44, v45
	v_cvt_pk_bf16_f32 v23, v46, v47
	global_store_dwordx2 v[16:17], v[18:19], off offset:512 sc1
	v_cvt_pk_bf16_f32 v18, v40, v41
	v_cvt_pk_bf16_f32 v19, v42, v43
	global_store_dwordx2 v[12:13], v[14:15], off offset:512 sc1
	v_cvt_pk_bf16_f32 v14, v36, v37
	v_cvt_pk_bf16_f32 v15, v38, v39
	global_store_dwordx2 v[8:9], v[10:11], off offset:512 sc1
	v_cvt_pk_bf16_f32 v10, v24, v25
	v_cvt_pk_bf16_f32 v11, v26, v27
	global_store_dwordx2 v[0:1], v[2:3], off offset:512 sc1
	s_waitcnt vmcnt(25)
	v_cvt_pk_bf16_f32 v2, v126, v127
	v_cvt_pk_bf16_f32 v3, v128, v129
	global_store_dwordx2 v[134:135], v[60:61], off offset:1024 sc1
	global_store_dwordx2 v[32:33], v[34:35], off offset:1024 sc1
	global_store_dwordx2 v[20:21], v[22:23], off offset:1024 sc1
	global_store_dwordx2 v[16:17], v[18:19], off offset:1024 sc1
	global_store_dwordx2 v[12:13], v[14:15], off offset:1024 sc1
	global_store_dwordx2 v[8:9], v[10:11], off offset:1024 sc1
	global_store_dwordx2 v[0:1], v[2:3], off offset:1024 sc1
	s_waitcnt vmcnt(31)
	v_cvt_pk_bf16_f32 v2, v130, v131
	v_cvt_pk_bf16_f32 v3, v132, v133
	global_store_dwordx2 v[0:1], v[2:3], off offset:1536 sc1
